# k46 + POST rope arms branch-free via per-lane merged tables (15 of 25 sections): removes divergent control flow, second arm and a wait per section
# speedup vs baseline: 1.0042x; 1.0042x over previous
; #define LAS __attribute__((address_space(3)))
; DI unsigned pk2(float lo, float hi) { f32x2 x = {lo, hi}; return __builtin_bit_cast(unsigned, __builtin_convertvector(x, bf16x2_t)); }
; DI float sum32(float v) { v += __shfl_xor(v, 16); return sum16(v); }
; DI f32x2 unpk(unsigned w) { f32x2 r = {bflo(w), bfhi(w)}; return r; }
; template <int HP> DI void rope2(f32x2& x, int hl, const LAS f32x2* cs) {
;   const float pa = __shfl_xor(x[0], HP), pb = __shfl_xor(x[1], HP);
;   if (hl < HP) { const f32x2 c0 = cs[2 * hl], c1 = cs[2 * hl + 1]; x[0] = x[0] * c0[0] - pa * c0[1]; x[1] = x[1] * c1[0] - pb * c1[1]; }
;   else if (hl < 2 * HP) { const f32x2 c0 = cs[2 * (hl - HP)], c1 = cs[2 * (hl - HP) + 1]; x[0] = x[0] * c0[0] + pa * c0[1]; x[1] = x[1] * c1[0] + pb * c1[1]; }
; }
; DI void post_unit(const Params& p, int l, int unit, LAS unsigned char* lds) {
;     ...
;   for (int tp = 0; tp < 4; ++tp) {
;     constexpr int segcol[16] = {C_QA, C_QA + 128, C_KA, C_QI, C_QI + 128, C_QI + 256, C_QI + 384, C_KI, C_QB, C_QB + 128, C_KB, C_KB + 128, C_QC, C_QC + 128, C_KC, C_KC + 128};
;     unsigned raw2[2][16];
; #pragma unroll
;     for (int hf = 0; hf < 2; ++hf) { const u16* rowl = proj + (tok0 + w * 8 + 2 * tp + hf) * NP;
; #pragma unroll
;       for (int s = 0; s < 16; ++s) raw2[hf][s] = *(const unsigned*)(rowl + segcol[s] + 2 * lane); }
; #pragma unroll
;     for (int hf = 0; hf < 2; ++hf) {
;     const int t = w * 8 + 2 * tp + hf; u16* row = proj + (tok0 + t) * NP;
; #pragma unroll
;     for (int s = 0; s < 16; ++s) {
;       f32x2 x = unpk(raw2[hf][s]); u16* pp = row + segcol[s] + 2 * lane;
;       if (s < 2) {
;         const float rs = rsqrtf(sum32(x[0] * x[0] + x[1] * x[1]) * (1.0f / 64.0f) + EPS);
;         x[0] *= rs * qna[2 * hl]; x[1] *= rs * qna[2 * hl + 1]; rope2<4>(x, hl, cs16 + t * 8);
;         x *= LOG2E * 0.125f; *(unsigned*)pp = pk2(x[0], x[1]);
.LBB0_150:
	ds_read_b128 v[208:211], v35
	ds_read_b128 v[212:215], v35 offset:64
	ds_read_b128 v[216:219], v39
	ds_read_b128 v[220:223], v39 offset:256
	ds_read_b128 v[224:227], v40
	ds_read_b128 v[228:231], v40 offset:32
	ds_read_b128 v[232:235], v35 offset:128
	ds_read_b128 v[236:239], v39 offset:512
	ds_read_b128 v[240:243], v40 offset:64
	s_waitcnt lgkmcnt(0)
	s_orn2_b64 s[98:99], s[14:15], s[12:13]
	s_orn2_b64 s[100:101], s[8:9], s[6:7]
	v_cndmask_b32_e64 v80, v212, v208, s[12:13]
	v_cndmask_b32_e64 v80, 1.0, v80, s[98:99]
	v_cndmask_b32_e64 v81, v214, v210, s[12:13]
	v_cndmask_b32_e64 v81, 1.0, v81, s[98:99]
	v_cndmask_b32_e64 v82, -v213, v209, s[12:13]
	v_cndmask_b32_e64 v82, 0, v82, s[98:99]
	v_cndmask_b32_e64 v83, -v215, v211, s[12:13]
	v_cndmask_b32_e64 v83, 0, v83, s[98:99]
	v_cndmask_b32_e64 v84, v228, v224, s[6:7]
	v_cndmask_b32_e64 v84, 1.0, v84, s[100:101]
	v_cndmask_b32_e64 v85, v230, v226, s[6:7]
	v_cndmask_b32_e64 v85, 1.0, v85, s[100:101]
	v_cndmask_b32_e64 v86, -v229, v225, s[6:7]
	v_cndmask_b32_e64 v86, 0, v86, s[100:101]
	v_cndmask_b32_e64 v87, -v231, v227, s[6:7]
	v_cndmask_b32_e64 v87, 0, v87, s[100:101]
	v_cndmask_b32_e64 v88, v232, v212, s[12:13]
	v_cndmask_b32_e64 v88, 1.0, v88, s[98:99]
	v_cndmask_b32_e64 v89, v234, v214, s[12:13]
	v_cndmask_b32_e64 v89, 1.0, v89, s[98:99]
	v_cndmask_b32_e64 v90, -v233, v213, s[12:13]
	v_cndmask_b32_e64 v90, 0, v90, s[98:99]
	v_cndmask_b32_e64 v91, -v235, v215, s[12:13]
	v_cndmask_b32_e64 v91, 0, v91, s[98:99]
	v_cndmask_b32_e64 v92, v240, v228, s[6:7]
	v_cndmask_b32_e64 v92, 1.0, v92, s[100:101]
	v_cndmask_b32_e64 v93, v242, v230, s[6:7]
	v_cndmask_b32_e64 v93, 1.0, v93, s[100:101]
	v_cndmask_b32_e64 v94, -v241, v229, s[6:7]
	v_cndmask_b32_e64 v94, 0, v94, s[100:101]
	v_cndmask_b32_e64 v95, -v243, v231, s[6:7]
	v_cndmask_b32_e64 v95, 0, v95, s[100:101]
	v_lshl_add_u64 v[18:19], v[12:13], 0, v[0:1]
	v_add_co_u32_e32 v20, vcc, 0xa000000, v18
	s_mov_b32 s2, 0xa001000
	s_waitcnt lgkmcnt(0)
	v_addc_co_u32_e32 v21, vcc, 0, v19, vcc
	global_load_dword v49, v[20:21], off
	v_add_co_u32_e32 v22, vcc, s2, v18
	s_mov_b32 s2, 0xa003000
	s_nop 0
	v_addc_co_u32_e32 v23, vcc, 0, v19, vcc
	v_add_co_u32_e32 v42, vcc, s77, v18
	global_load_dword v59, v[20:21], off offset:512
	global_load_dword v70, v[20:21], off offset:768
	global_load_dword v69, v[20:21], off offset:1024
	global_load_dword v68, v[20:21], off offset:1280
	global_load_dword v67, v[20:21], off offset:1536
	global_load_dword v58, v[20:21], off offset:1792
	global_load_dword v71, v[20:21], off offset:256
	v_addc_co_u32_e32 v43, vcc, 0, v19, vcc
	global_load_dword v56, v[20:21], off offset:2432
	global_load_dword v66, v[20:21], off offset:2688
	global_load_dword v65, v[20:21], off offset:2944
	global_load_dword v64, v[20:21], off offset:3200
	global_load_dword v54, v[22:23], off offset:384
	global_load_dword v63, v[22:23], off offset:640
	global_load_dword v62, v[22:23], off offset:896
	global_load_dword v61, v[22:23], off offset:1152
	v_add_co_u32_e32 v20, vcc, s2, v18
	global_load_dword v60, v[42:43], off offset:512
	global_load_dword v57, v[42:43], off offset:768
	global_load_dword v55, v[42:43], off offset:1024
	global_load_dword v53, v[42:43], off offset:1280
	global_load_dword v52, v[42:43], off offset:1536
	global_load_dword v51, v[42:43], off offset:1792
	global_load_dword v50, v[42:43], off offset:2048
	global_load_dword v48, v[42:43], off offset:2304
	v_addc_co_u32_e32 v21, vcc, 0, v19, vcc
	global_load_dword v47, v[42:43], off offset:2944
	global_load_dword v46, v[42:43], off offset:3200
	global_load_dword v45, v[42:43], off offset:3456
	global_load_dword v44, v[42:43], off offset:3712
	s_nop 0
	global_load_dword v43, v[20:21], off offset:896
	global_load_dword v42, v[20:21], off offset:1152
	global_load_dword v41, v[20:21], off offset:1408
	global_load_dword v3, v[20:21], off offset:1664
	s_waitcnt vmcnt(31)
	v_and_b32_e32 v21, 0xffff0000, v49
	v_lshlrev_b32_e32 v20, 16, v49
	v_pk_mul_f32 v[22:23], v[20:21], v[20:21]
	s_nop 0
	v_add_f32_e32 v22, v22, v23
	v_mov_b32_e32 v23, v22
	s_nop 1
	v_permlane16_swap_b32_e32 v22, v23
	v_add_f32_e32 v22, v22, v23
	s_nop 1
	v_add_f32_dpp v22, v22, v22 row_ror:8 row_mask:0xf bank_mask:0xf
	s_nop 1
	v_add_f32_dpp v22, v22, v22 row_ror:4 row_mask:0xf bank_mask:0xf
	s_nop 1
	v_add_f32_dpp v22, v22, v22 quad_perm:[2,3,0,1] row_mask:0xf bank_mask:0xf
	s_nop 1
	v_add_f32_dpp v22, v22, v22 quad_perm:[1,0,3,2] row_mask:0xf bank_mask:0xf
	v_fmamk_f32 v22, v22, 0x3c800000, v170
	v_mul_f32_e32 v23, 0x4b800000, v22
	v_cmp_gt_f32_e32 vcc, s33, v22
	s_nop 1
	v_cndmask_b32_e32 v22, v22, v23, vcc
	v_rsq_f32_e32 v22, v22
	s_nop 0
	v_mul_f32_e32 v23, 0x45800000, v22
	v_cndmask_b32_e32 v22, v22, v23, vcc
	v_pk_mul_f32 v[22:23], v[4:5], v[22:23] op_sel_hi:[1,0]
	s_nop 0
	v_pk_mul_f32 v[22:23], v[22:23], v[20:21]
	ds_bpermute_b32 v20, v28, v22
	ds_bpermute_b32 v21, v28, v23
	v_add_u32_e32 v49, 0, v35
	s_waitcnt lgkmcnt(0)
	v_mul_f32_e32 v22, v22, v80
	v_mul_f32_e32 v23, v23, v81
	v_fmac_f32_e32 v22, v82, v20
	v_fmac_f32_e32 v23, v83, v21
	s_mov_b64 s[2:3], 0xa000000
	s_waitcnt lgkmcnt(0)
	v_lshl_add_u64 v[20:21], v[18:19], 0, s[2:3]
	s_mov_b32 s2, 0x3e38aa3b
	v_pk_mul_f32 v[22:23], v[22:23], s[2:3] op_sel_hi:[1,0]
	s_nop 0
	v_cvt_pk_bf16_f32 v22, v22, v23
	global_store_dword v[20:21], v22, off
	s_waitcnt vmcnt(25)
; #define LAS __attribute__((address_space(3)))
; DI unsigned pk2(float lo, float hi) { f32x2 x = {lo, hi}; return __builtin_bit_cast(unsigned, __builtin_convertvector(x, bf16x2_t)); }
; DI float sum32(float v) { v += __shfl_xor(v, 16); return sum16(v); }
; DI float sum64(float v) { v += __shfl_xor(v, 32); return sum32(v); }
; DI f32x2 unpk(unsigned w) { f32x2 r = {bflo(w), bfhi(w)}; return r; }
; DI void post_unit(const Params& p, int l, int unit, LAS unsigned char* lds) {
;     ...
;     for (int s = 0; s < 16; ++s) {
;       f32x2 x = unpk(raw2[hf][s]); u16* pp = row + segcol[s] + 2 * lane;
;       if (s < 2) {
;         const float rs = rsqrtf(sum32(x[0] * x[0] + x[1] * x[1]) * (1.0f / 64.0f) + EPS);
;         x[0] *= rs * qna[2 * hl]; x[1] *= rs * qna[2 * hl + 1]; rope2<4>(x, hl, cs16 + t * 8);
;         x *= LOG2E * 0.125f; *(unsigned*)pp = pk2(x[0], x[1]);
;       } else if (s == 2) {
;         const float rs = rsqrtf(sum64(x[0] * x[0] + x[1] * x[1]) * (1.0f / 128.0f) + EPS);
;         *(LAS unsigned*)(At + t * 272 + lane * 4) = pk2(x[0] * rs, x[1] * rs);
;       } else if (s < 7) {
;         rope2<4>(x, hl, cs16 + t * 8); *(unsigned*)pp = pk2(x[0], x[1]);
;       } else if (s == 7) {
;         const float rs = rsqrtf(sum32(x[0] * x[0] + x[1] * x[1]) * (1.0f / 64.0f) + EPS);
;         x *= rs; rope2<4>(x, hl, cs16 + t * 8); if (lane < 32) *(unsigned*)((u16*)(p.ws + WS_KIC) + (tok0 + t) * 64 + 2 * lane) = pk2(x[0], x[1]);
	v_and_b32_e32 v21, 0xffff0000, v71
	v_lshlrev_b32_e32 v20, 16, v71
	v_pk_mul_f32 v[22:23], v[20:21], v[20:21]
	s_nop 0
	v_add_f32_e32 v22, v22, v23
	v_mov_b32_e32 v23, v22
	s_nop 1
	v_permlane16_swap_b32_e32 v22, v23
	v_add_f32_e32 v22, v22, v23
	s_nop 1
	v_add_f32_dpp v22, v22, v22 row_ror:8 row_mask:0xf bank_mask:0xf
	s_nop 1
	v_add_f32_dpp v22, v22, v22 row_ror:4 row_mask:0xf bank_mask:0xf
	s_nop 1
	v_add_f32_dpp v22, v22, v22 quad_perm:[2,3,0,1] row_mask:0xf bank_mask:0xf
	s_nop 1
	v_add_f32_dpp v22, v22, v22 quad_perm:[1,0,3,2] row_mask:0xf bank_mask:0xf
	v_fmamk_f32 v22, v22, 0x3c800000, v170
	v_cmp_gt_f32_e32 vcc, s33, v22
	v_mul_f32_e32 v23, 0x4b800000, v22
	s_nop 0
	v_cndmask_b32_e32 v22, v22, v23, vcc
	v_rsq_f32_e32 v22, v22
	s_nop 0
	v_mul_f32_e32 v23, 0x45800000, v22
	v_cndmask_b32_e32 v22, v22, v23, vcc
	v_pk_mul_f32 v[22:23], v[4:5], v[22:23] op_sel_hi:[1,0]
	s_nop 0
	v_pk_mul_f32 v[22:23], v[22:23], v[20:21]
	ds_bpermute_b32 v20, v28, v22
	ds_bpermute_b32 v21, v28, v23
	s_waitcnt lgkmcnt(0)
	v_mul_f32_e32 v22, v22, v80
	v_mul_f32_e32 v23, v23, v81
	v_fmac_f32_e32 v22, v82, v20
	v_fmac_f32_e32 v23, v83, v21
	s_mov_b64 s[2:3], 0xa000100
	s_waitcnt lgkmcnt(0)
	v_lshl_add_u64 v[20:21], v[18:19], 0, s[2:3]
	s_mov_b32 s2, 0x3e38aa3b
	v_pk_mul_f32 v[22:23], v[22:23], s[2:3] op_sel_hi:[1,0]
	s_nop 0
	v_cvt_pk_bf16_f32 v22, v22, v23
	global_store_dword v[20:21], v22, off
	v_lshlrev_b32_e32 v20, 16, v59
	v_and_b32_e32 v21, 0xffff0000, v59
	v_pk_mul_f32 v[22:23], v[20:21], v[20:21]
	v_add_u32_e32 v59, 0, v33
	v_add_f32_e32 v22, v22, v23
	v_mov_b32_e32 v23, v22
	s_nop 1
	v_permlane32_swap_b32_e32 v22, v23
	v_add_f32_e32 v22, v22, v23
	v_mov_b32_e32 v23, v22
	s_nop 1
	v_permlane16_swap_b32_e32 v22, v23
	v_add_f32_e32 v22, v22, v23
	s_nop 1
	v_add_f32_dpp v22, v22, v22 row_ror:8 row_mask:0xf bank_mask:0xf
	s_nop 1
	v_add_f32_dpp v22, v22, v22 row_ror:4 row_mask:0xf bank_mask:0xf
	s_nop 1
	v_add_f32_dpp v22, v22, v22 quad_perm:[2,3,0,1] row_mask:0xf bank_mask:0xf
	s_nop 1
	v_add_f32_dpp v22, v22, v22 quad_perm:[1,0,3,2] row_mask:0xf bank_mask:0xf
	v_fmamk_f32 v22, v22, 0x3c000000, v170
	v_cmp_gt_f32_e32 vcc, s33, v22
	v_mul_f32_e32 v23, 0x4b800000, v22
	s_nop 0
	v_cndmask_b32_e32 v22, v22, v23, vcc
	v_rsq_f32_e32 v22, v22
	s_nop 0
	v_mul_f32_e32 v23, 0x45800000, v22
	v_cndmask_b32_e32 v22, v22, v23, vcc
	v_pk_mul_f32 v[20:21], v[22:23], v[20:21] op_sel_hi:[0,1]
	v_cvt_pk_bf16_f32 v20, v20, v21
	ds_write_b32 v59, v20
	v_lshlrev_b32_e32 v20, 16, v70
	v_and_b32_e32 v21, 0xffff0000, v70
	ds_bpermute_b32 v70, v28, v20
	ds_bpermute_b32 v23, v28, v21
	s_waitcnt lgkmcnt(0)
	v_mul_f32_e32 v20, v20, v80
	v_mul_f32_e32 v21, v21, v81
	v_fmac_f32_e32 v20, v82, v70
	v_fmac_f32_e32 v21, v83, v23
	s_mov_b64 s[2:3], 0xa000300
	s_waitcnt lgkmcnt(0)
	v_lshl_add_u64 v[22:23], v[18:19], 0, s[2:3]
	v_cvt_pk_bf16_f32 v20, v20, v21
	global_store_dword v[22:23], v20, off
	v_lshlrev_b32_e32 v20, 16, v69
	v_and_b32_e32 v21, 0xffff0000, v69
	ds_bpermute_b32 v69, v28, v20
	ds_bpermute_b32 v23, v28, v21
	s_waitcnt lgkmcnt(0)
	v_mul_f32_e32 v20, v20, v80
	v_mul_f32_e32 v21, v21, v81
	v_fmac_f32_e32 v20, v82, v69
	v_fmac_f32_e32 v21, v83, v23
	s_mov_b64 s[2:3], 0xa000400
	s_waitcnt lgkmcnt(0)
	v_lshl_add_u64 v[22:23], v[18:19], 0, s[2:3]
	v_cvt_pk_bf16_f32 v20, v20, v21
	global_store_dword v[22:23], v20, off
	v_lshlrev_b32_e32 v20, 16, v68
	v_and_b32_e32 v21, 0xffff0000, v68
	ds_bpermute_b32 v68, v28, v20
	ds_bpermute_b32 v23, v28, v21
	s_waitcnt lgkmcnt(0)
	v_mul_f32_e32 v20, v20, v80
	v_mul_f32_e32 v21, v21, v81
	v_fmac_f32_e32 v20, v82, v68
	v_fmac_f32_e32 v21, v83, v23
	s_mov_b64 s[2:3], 0xa000500
	s_waitcnt lgkmcnt(0)
	v_lshl_add_u64 v[22:23], v[18:19], 0, s[2:3]
	v_cvt_pk_bf16_f32 v20, v20, v21
	global_store_dword v[22:23], v20, off
	v_lshlrev_b32_e32 v20, 16, v67
	v_and_b32_e32 v21, 0xffff0000, v67
	ds_bpermute_b32 v67, v28, v20
	ds_bpermute_b32 v23, v28, v21
	s_waitcnt lgkmcnt(0)
	v_mul_f32_e32 v20, v20, v80
	v_mul_f32_e32 v21, v21, v81
	v_fmac_f32_e32 v20, v82, v67
	v_fmac_f32_e32 v21, v83, v23
	s_mov_b64 s[2:3], 0xa000600
	s_waitcnt lgkmcnt(0)
	v_lshl_add_u64 v[22:23], v[18:19], 0, s[2:3]
	v_cvt_pk_bf16_f32 v20, v20, v21
	global_store_dword v[22:23], v20, off
	v_lshlrev_b32_e32 v20, 16, v58
	v_and_b32_e32 v21, 0xffff0000, v58
	v_pk_mul_f32 v[22:23], v[20:21], v[20:21]
	s_nop 0
	v_add_f32_e32 v22, v22, v23
	v_mov_b32_e32 v23, v22
	s_nop 1
	v_permlane16_swap_b32_e32 v22, v23
	v_add_f32_e32 v22, v22, v23
	s_nop 1
	v_add_f32_dpp v22, v22, v22 row_ror:8 row_mask:0xf bank_mask:0xf
	s_nop 1
	v_add_f32_dpp v22, v22, v22 row_ror:4 row_mask:0xf bank_mask:0xf
	s_nop 1
	v_add_f32_dpp v22, v22, v22 quad_perm:[2,3,0,1] row_mask:0xf bank_mask:0xf
	s_nop 1
	v_add_f32_dpp v22, v22, v22 quad_perm:[1,0,3,2] row_mask:0xf bank_mask:0xf
	v_fmamk_f32 v22, v22, 0x3c800000, v170
	v_cmp_gt_f32_e32 vcc, s33, v22
	v_mul_f32_e32 v23, 0x4b800000, v22
	s_nop 0
	v_cndmask_b32_e32 v22, v22, v23, vcc
	v_rsq_f32_e32 v22, v22
	s_nop 0
	v_mul_f32_e32 v23, 0x45800000, v22
	v_cndmask_b32_e32 v22, v22, v23, vcc
	v_pk_mul_f32 v[20:21], v[22:23], v[20:21] op_sel_hi:[0,1]
	ds_bpermute_b32 v22, v28, v20
	ds_bpermute_b32 v23, v28, v21
	s_and_saveexec_b64 s[2:3], s[12:13]
	s_xor_b64 s[18:19], exec, s[2:3]
	s_cbranch_execz .LBB0_314
	s_and_saveexec_b64 s[30:31], s[14:15]
	s_cbranch_execz .LBB0_189
	s_waitcnt lgkmcnt(0)
	v_mul_f32_e32 v20, v20, v208
	v_mul_f32_e32 v21, v210, v21
	v_fmac_f32_e32 v20, v209, v22
	v_fmac_f32_e32 v21, v211, v23

; DI unsigned pk2(float lo, float hi) { f32x2 x = {lo, hi}; return __builtin_bit_cast(unsigned, __builtin_convertvector(x, bf16x2_t)); }
; DI float sum16(float v) { v += __shfl_xor(v, 8); v += __shfl_xor(v, 4); v += __shfl_xor(v, 2); v += __shfl_xor(v, 1); return v; }
; DI void post_unit(const Params& p, int l, int unit, LAS unsigned char* lds) {
;     ...
;       } else if (s < 12) {
;         rope2<16>(x, hl, cs64 + t * 32);
;         const int hd = ((s & 1) ? 2 : 0) + hsel;
;         const float lg = log1pf(-exp2f(-5.0f - (float)hd));
;         const float f = (s < 10) ? expf(lg * (float)(t + 1)) : expf(lg * (float)(63 - t)) * 0.125f;
;         x *= f; *(unsigned*)pp = pk2(x[0], x[1]);
;       } else {
;         const float* gn = (s < 14) ? qnc : knc;
;         const float rs = rsqrtf(sum16(x[0] * x[0] + x[1] * x[1]) * (1.0f / 32.0f) + EPS);
;         x[0] *= rs * gn[2 * hl16]; x[1] *= rs * gn[2 * hl16 + 1]; rope2<2>(x, hl16, cs8 + t * 4);
;         if (s < 14) x *= LOG2E * 0.17677669529663687f;
;         *(unsigned*)pp = pk2(x[0], x[1]);
.LBB0_208:
	s_or_b64 exec, exec, s[18:19]
	s_waitcnt lgkmcnt(1)
	v_mul_f32_e32 v64, v32, v65
	v_mul_f32_e32 v65, 0x3fb8aa3b, v64
	v_fma_f32 v66, v64, s64, -v65
	v_rndne_f32_e32 v67, v65
	v_fmac_f32_e32 v66, 0x32a5705f, v64
	v_sub_f32_e32 v65, v65, v67
	v_add_f32_e32 v65, v65, v66
	v_exp_f32_e32 v65, v65
	v_cvt_i32_f32_e32 v66, v67
	v_cmp_ngt_f32_e32 vcc, s65, v64
	s_mov_b64 s[2:3], 0xa000c80
	s_waitcnt lgkmcnt(0)
	v_lshl_add_u64 v[20:21], v[18:19], 0, s[2:3]
	v_ldexp_f32 v65, v65, v66
	v_cndmask_b32_e32 v65, 0, v65, vcc
	v_cmp_nlt_f32_e32 vcc, s89, v64
	s_nop 1
	v_cndmask_b32_e32 v64, v177, v65, vcc
	v_mul_f32_e32 v64, 0x3e000000, v64
	v_pk_mul_f32 v[22:23], v[64:65], v[22:23] op_sel_hi:[0,1]
	v_cvt_pk_bf16_f32 v22, v22, v23
	global_store_dword v[20:21], v22, off
	s_waitcnt vmcnt(29)
	v_lshlrev_b32_e32 v20, 16, v54
	v_and_b32_e32 v21, 0xffff0000, v54
	v_pk_mul_f32 v[22:23], v[20:21], v[20:21]
	s_nop 0
	v_add_f32_e32 v22, v22, v23
	s_nop 1
	v_add_f32_dpp v22, v22, v22 row_ror:8 row_mask:0xf bank_mask:0xf
	s_nop 1
	v_add_f32_dpp v22, v22, v22 row_ror:4 row_mask:0xf bank_mask:0xf
	s_nop 1
	v_add_f32_dpp v22, v22, v22 quad_perm:[2,3,0,1] row_mask:0xf bank_mask:0xf
	s_nop 1
	v_add_f32_dpp v22, v22, v22 quad_perm:[1,0,3,2] row_mask:0xf bank_mask:0xf
	v_fmamk_f32 v22, v22, 0x3d000000, v170
	v_cmp_gt_f32_e32 vcc, s33, v22
	v_mul_f32_e32 v23, 0x4b800000, v22
	s_nop 0
	v_cndmask_b32_e32 v22, v22, v23, vcc
	v_rsq_f32_e32 v22, v22
	s_nop 0
	v_mul_f32_e32 v23, 0x45800000, v22
	v_cndmask_b32_e32 v22, v22, v23, vcc
	v_pk_mul_f32 v[22:23], v[6:7], v[22:23] op_sel_hi:[1,0]
	s_nop 0
	v_pk_mul_f32 v[22:23], v[22:23], v[20:21]
	ds_bpermute_b32 v20, v29, v22
	ds_bpermute_b32 v21, v29, v23
	v_add_u32_e32 v54, 0, v40
	s_waitcnt lgkmcnt(0)
	v_mul_f32_e32 v22, v22, v84
	v_mul_f32_e32 v23, v23, v85
	v_fmac_f32_e32 v22, v86, v20
	v_fmac_f32_e32 v23, v87, v21
	s_mov_b64 s[2:3], 0xa001180
	s_waitcnt lgkmcnt(0)
	v_lshl_add_u64 v[20:21], v[18:19], 0, s[2:3]
	s_mov_b32 s2, 0x3e8293ee
	v_pk_mul_f32 v[22:23], v[22:23], s[2:3] op_sel_hi:[1,0]
	s_nop 0
	v_cvt_pk_bf16_f32 v22, v22, v23
	global_store_dword v[20:21], v22, off
	s_waitcnt vmcnt(29)
	v_lshlrev_b32_e32 v20, 16, v63
	v_and_b32_e32 v21, 0xffff0000, v63
	v_pk_mul_f32 v[22:23], v[20:21], v[20:21]
	s_nop 0
	v_add_f32_e32 v22, v22, v23
	s_nop 1
	v_add_f32_dpp v22, v22, v22 row_ror:8 row_mask:0xf bank_mask:0xf
	s_nop 1
	v_add_f32_dpp v22, v22, v22 row_ror:4 row_mask:0xf bank_mask:0xf
	s_nop 1
	v_add_f32_dpp v22, v22, v22 quad_perm:[2,3,0,1] row_mask:0xf bank_mask:0xf
	s_nop 1
	v_add_f32_dpp v22, v22, v22 quad_perm:[1,0,3,2] row_mask:0xf bank_mask:0xf
	v_fmamk_f32 v22, v22, 0x3d000000, v170
	v_cmp_gt_f32_e32 vcc, s33, v22
	v_mul_f32_e32 v23, 0x4b800000, v22
	s_nop 0
	v_cndmask_b32_e32 v22, v22, v23, vcc
	v_rsq_f32_e32 v22, v22
	s_nop 0
	v_mul_f32_e32 v23, 0x45800000, v22
	v_cndmask_b32_e32 v22, v22, v23, vcc
	v_pk_mul_f32 v[22:23], v[6:7], v[22:23] op_sel_hi:[1,0]
	s_nop 0
	v_pk_mul_f32 v[22:23], v[22:23], v[20:21]
	ds_bpermute_b32 v20, v29, v22
	ds_bpermute_b32 v21, v29, v23
	s_waitcnt lgkmcnt(0)
	v_mul_f32_e32 v22, v22, v84
	v_mul_f32_e32 v23, v23, v85
	v_fmac_f32_e32 v22, v86, v20
	v_fmac_f32_e32 v23, v87, v21
	s_mov_b64 s[2:3], 0xa001280
	s_waitcnt lgkmcnt(0)
	v_lshl_add_u64 v[20:21], v[18:19], 0, s[2:3]
	s_mov_b32 s2, 0x3e8293ee
	v_pk_mul_f32 v[22:23], v[22:23], s[2:3] op_sel_hi:[1,0]
	s_nop 0
	v_cvt_pk_bf16_f32 v22, v22, v23
	global_store_dword v[20:21], v22, off
	s_waitcnt vmcnt(29)
	v_lshlrev_b32_e32 v20, 16, v62
	v_and_b32_e32 v21, 0xffff0000, v62
	v_pk_mul_f32 v[22:23], v[20:21], v[20:21]
	s_nop 0
	v_add_f32_e32 v22, v22, v23
	s_nop 1
	v_add_f32_dpp v22, v22, v22 row_ror:8 row_mask:0xf bank_mask:0xf
	s_nop 1
	v_add_f32_dpp v22, v22, v22 row_ror:4 row_mask:0xf bank_mask:0xf
	s_nop 1
	v_add_f32_dpp v22, v22, v22 quad_perm:[2,3,0,1] row_mask:0xf bank_mask:0xf
	s_nop 1
	v_add_f32_dpp v22, v22, v22 quad_perm:[1,0,3,2] row_mask:0xf bank_mask:0xf
	v_fmamk_f32 v22, v22, 0x3d000000, v170
	v_cmp_gt_f32_e32 vcc, s33, v22
	v_mul_f32_e32 v23, 0x4b800000, v22
	s_nop 0
	v_cndmask_b32_e32 v22, v22, v23, vcc
	v_rsq_f32_e32 v22, v22
	s_nop 0
	v_mul_f32_e32 v23, 0x45800000, v22
	v_cndmask_b32_e32 v22, v22, v23, vcc
	v_pk_mul_f32 v[22:23], v[8:9], v[22:23] op_sel_hi:[1,0]
	s_nop 0
	v_pk_mul_f32 v[22:23], v[22:23], v[20:21]
	ds_bpermute_b32 v20, v29, v22
	ds_bpermute_b32 v21, v29, v23
	s_waitcnt lgkmcnt(0)
	v_mul_f32_e32 v22, v22, v84
	v_mul_f32_e32 v23, v23, v85
	v_fmac_f32_e32 v22, v86, v20
	v_fmac_f32_e32 v23, v87, v21
	s_mov_b64 s[2:3], 0xa001380
	s_waitcnt lgkmcnt(0)
	v_lshl_add_u64 v[20:21], v[18:19], 0, s[2:3]
	v_cvt_pk_bf16_f32 v22, v22, v23
	global_store_dword v[20:21], v22, off
	s_waitcnt vmcnt(29)
	v_lshlrev_b32_e32 v20, 16, v61
	v_and_b32_e32 v21, 0xffff0000, v61
	v_pk_mul_f32 v[22:23], v[20:21], v[20:21]
	s_nop 0
	v_add_f32_e32 v22, v22, v23
	s_nop 1
	v_add_f32_dpp v22, v22, v22 row_ror:8 row_mask:0xf bank_mask:0xf
	s_nop 1
	v_add_f32_dpp v22, v22, v22 row_ror:4 row_mask:0xf bank_mask:0xf
	s_nop 1
	v_add_f32_dpp v22, v22, v22 quad_perm:[2,3,0,1] row_mask:0xf bank_mask:0xf
	s_nop 1
	v_add_f32_dpp v22, v22, v22 quad_perm:[1,0,3,2] row_mask:0xf bank_mask:0xf
	v_fmamk_f32 v22, v22, 0x3d000000, v170
	v_cmp_gt_f32_e32 vcc, s33, v22
	v_mul_f32_e32 v23, 0x4b800000, v22
	s_nop 0
	v_cndmask_b32_e32 v22, v22, v23, vcc
	v_rsq_f32_e32 v22, v22
	s_nop 0
	v_mul_f32_e32 v23, 0x45800000, v22
	v_cndmask_b32_e32 v22, v22, v23, vcc
	v_pk_mul_f32 v[22:23], v[8:9], v[22:23] op_sel_hi:[1,0]
	s_nop 0
	v_pk_mul_f32 v[22:23], v[22:23], v[20:21]
	ds_bpermute_b32 v20, v29, v22
	ds_bpermute_b32 v21, v29, v23
	s_waitcnt lgkmcnt(0)
; #define LAS __attribute__((address_space(3)))
; DI unsigned pk2(float lo, float hi) { f32x2 x = {lo, hi}; return __builtin_bit_cast(unsigned, __builtin_convertvector(x, bf16x2_t)); }
; DI float sum16(float v) { v += __shfl_xor(v, 8); v += __shfl_xor(v, 4); v += __shfl_xor(v, 2); v += __shfl_xor(v, 1); return v; }
; DI float sum32(float v) { v += __shfl_xor(v, 16); return sum16(v); }
; DI float sum64(float v) { v += __shfl_xor(v, 32); return sum32(v); }
; DI f32x2 unpk(unsigned w) { f32x2 r = {bflo(w), bfhi(w)}; return r; }
; DI void post_unit(const Params& p, int l, int unit, LAS unsigned char* lds) {
;     ...
;     for (int s = 0; s < 16; ++s) {
;       f32x2 x = unpk(raw2[hf][s]); u16* pp = row + segcol[s] + 2 * lane;
;       if (s < 2) {
;         const float rs = rsqrtf(sum32(x[0] * x[0] + x[1] * x[1]) * (1.0f / 64.0f) + EPS);
;         x[0] *= rs * qna[2 * hl]; x[1] *= rs * qna[2 * hl + 1]; rope2<4>(x, hl, cs16 + t * 8);
;         x *= LOG2E * 0.125f; *(unsigned*)pp = pk2(x[0], x[1]);
;       } else if (s == 2) {
;         const float rs = rsqrtf(sum64(x[0] * x[0] + x[1] * x[1]) * (1.0f / 128.0f) + EPS);
;         *(LAS unsigned*)(At + t * 272 + lane * 4) = pk2(x[0] * rs, x[1] * rs);
;       } else if (s < 7) {
;         rope2<4>(x, hl, cs16 + t * 8); *(unsigned*)pp = pk2(x[0], x[1]);
;     ...
;       } else {
;         const float* gn = (s < 14) ? qnc : knc;
;         const float rs = rsqrtf(sum16(x[0] * x[0] + x[1] * x[1]) * (1.0f / 32.0f) + EPS);
;         x[0] *= rs * gn[2 * hl16]; x[1] *= rs * gn[2 * hl16 + 1]; rope2<2>(x, hl16, cs8 + t * 4);
;         if (s < 14) x *= LOG2E * 0.17677669529663687f;
;         *(unsigned*)pp = pk2(x[0], x[1]);
	v_mul_f32_e32 v22, v22, v84
	v_mul_f32_e32 v23, v23, v85
	v_fmac_f32_e32 v22, v86, v20
	v_fmac_f32_e32 v23, v87, v21
	s_mov_b64 s[2:3], 0xa001480
	v_lshl_add_u64 v[18:19], v[18:19], 0, s[2:3]
	s_waitcnt lgkmcnt(1)
	v_cvt_pk_bf16_f32 v20, v22, v23
	global_store_dword v[18:19], v20, off
	s_waitcnt vmcnt(29)
	v_and_b32_e32 v19, 0xffff0000, v60
	v_lshlrev_b32_e32 v18, 16, v60
	s_waitcnt lgkmcnt(0)
	v_pk_mul_f32 v[20:21], v[18:19], v[18:19]
	s_nop 0
	v_add_f32_e32 v20, v20, v21
	v_mov_b32_e32 v21, v20
	s_nop 1
	v_permlane16_swap_b32_e32 v20, v21
	v_add_f32_e32 v20, v20, v21
	s_nop 1
	v_add_f32_dpp v20, v20, v20 row_ror:8 row_mask:0xf bank_mask:0xf
	s_nop 1
	v_add_f32_dpp v20, v20, v20 row_ror:4 row_mask:0xf bank_mask:0xf
	s_nop 1
	v_add_f32_dpp v20, v20, v20 quad_perm:[2,3,0,1] row_mask:0xf bank_mask:0xf
	s_nop 1
	v_add_f32_dpp v20, v20, v20 quad_perm:[1,0,3,2] row_mask:0xf bank_mask:0xf
	v_fmamk_f32 v20, v20, 0x3c800000, v170
	v_cmp_gt_f32_e32 vcc, s33, v20
	v_mul_f32_e32 v21, 0x4b800000, v20
	s_nop 0
	v_cndmask_b32_e32 v20, v20, v21, vcc
	v_rsq_f32_e32 v20, v20
	s_nop 0
	v_mul_f32_e32 v21, 0x45800000, v20
	v_cndmask_b32_e32 v20, v20, v21, vcc
	v_pk_mul_f32 v[20:21], v[4:5], v[20:21] op_sel_hi:[1,0]
	s_nop 0
	v_pk_mul_f32 v[20:21], v[20:21], v[18:19]
	ds_bpermute_b32 v18, v28, v20
	ds_bpermute_b32 v19, v28, v21
	s_waitcnt lgkmcnt(0)
	v_mul_f32_e32 v20, v20, v88
	v_mul_f32_e32 v21, v21, v89
	v_fmac_f32_e32 v20, v90, v18
	v_fmac_f32_e32 v21, v91, v19
	s_mov_b32 s2, 0x3e38aa3b
	s_waitcnt lgkmcnt(0)
	v_lshl_add_u64 v[18:19], v[14:15], 0, v[0:1]
	v_pk_mul_f32 v[20:21], v[20:21], s[2:3] op_sel_hi:[1,0]
	s_nop 0
	v_cvt_pk_bf16_f32 v22, v20, v21
	v_add_co_u32_e32 v20, vcc, 0xa002000, v18
	s_nop 1
	v_addc_co_u32_e32 v21, vcc, 0, v19, vcc
	global_store_dword v[20:21], v22, off offset:512
	s_waitcnt vmcnt(29)
	v_and_b32_e32 v21, 0xffff0000, v57
	v_lshlrev_b32_e32 v20, 16, v57
	v_pk_mul_f32 v[22:23], v[20:21], v[20:21]
	s_nop 0
	v_add_f32_e32 v22, v22, v23
	v_mov_b32_e32 v23, v22
	s_nop 1
	v_permlane16_swap_b32_e32 v22, v23
	v_add_f32_e32 v22, v22, v23
	s_nop 1
	v_add_f32_dpp v22, v22, v22 row_ror:8 row_mask:0xf bank_mask:0xf
	s_nop 1
	v_add_f32_dpp v22, v22, v22 row_ror:4 row_mask:0xf bank_mask:0xf
	s_nop 1
	v_add_f32_dpp v22, v22, v22 quad_perm:[2,3,0,1] row_mask:0xf bank_mask:0xf
	s_nop 1
	v_add_f32_dpp v22, v22, v22 quad_perm:[1,0,3,2] row_mask:0xf bank_mask:0xf
	v_fmamk_f32 v22, v22, 0x3c800000, v170
	v_cmp_gt_f32_e32 vcc, s33, v22
	v_mul_f32_e32 v23, 0x4b800000, v22
	s_nop 0
	v_cndmask_b32_e32 v22, v22, v23, vcc
	v_rsq_f32_e32 v22, v22
	s_nop 0
	v_mul_f32_e32 v23, 0x45800000, v22
	v_cndmask_b32_e32 v22, v22, v23, vcc
	v_pk_mul_f32 v[22:23], v[4:5], v[22:23] op_sel_hi:[1,0]
	s_nop 0
	v_pk_mul_f32 v[22:23], v[22:23], v[20:21]
	ds_bpermute_b32 v20, v28, v22
	ds_bpermute_b32 v21, v28, v23
	s_waitcnt lgkmcnt(0)
	v_mul_f32_e32 v22, v22, v88
	v_mul_f32_e32 v23, v23, v89
	v_fmac_f32_e32 v22, v90, v20
	v_fmac_f32_e32 v23, v91, v21
	s_mov_b32 s2, 0x3e38aa3b
	s_waitcnt lgkmcnt(0)
	v_pk_mul_f32 v[20:21], v[22:23], s[2:3] op_sel_hi:[1,0]
	s_nop 0
	v_cvt_pk_bf16_f32 v22, v20, v21
	v_add_co_u32_e32 v20, vcc, 0xa002000, v18
	s_nop 1
	v_addc_co_u32_e32 v21, vcc, 0, v19, vcc
	global_store_dword v[20:21], v22, off offset:768
	s_waitcnt vmcnt(29)
	v_lshlrev_b32_e32 v20, 16, v55
	v_and_b32_e32 v21, 0xffff0000, v55
	v_pk_mul_f32 v[22:23], v[20:21], v[20:21]
	s_nop 0
	v_add_f32_e32 v22, v22, v23
	v_mov_b32_e32 v23, v22
	s_nop 1
	v_permlane32_swap_b32_e32 v22, v23
	v_add_f32_e32 v22, v22, v23
	v_mov_b32_e32 v23, v22
	s_nop 1
	v_permlane16_swap_b32_e32 v22, v23
	v_add_f32_e32 v22, v22, v23
	s_nop 1
	v_add_f32_dpp v22, v22, v22 row_ror:8 row_mask:0xf bank_mask:0xf
	s_nop 1
	v_add_f32_dpp v22, v22, v22 row_ror:4 row_mask:0xf bank_mask:0xf
	s_nop 1
	v_add_f32_dpp v22, v22, v22 quad_perm:[2,3,0,1] row_mask:0xf bank_mask:0xf
	s_nop 1
	v_add_f32_dpp v22, v22, v22 quad_perm:[1,0,3,2] row_mask:0xf bank_mask:0xf
	v_fmamk_f32 v22, v22, 0x3c000000, v170
	v_cmp_gt_f32_e32 vcc, s33, v22
	v_mul_f32_e32 v23, 0x4b800000, v22
	s_nop 0
	v_cndmask_b32_e32 v22, v22, v23, vcc
	v_rsq_f32_e32 v22, v22
	s_nop 0
	v_mul_f32_e32 v23, 0x45800000, v22
	v_cndmask_b32_e32 v22, v22, v23, vcc
	v_pk_mul_f32 v[20:21], v[22:23], v[20:21] op_sel_hi:[0,1]
	v_cvt_pk_bf16_f32 v20, v20, v21
	ds_write_b32 v59, v20 offset:272
	s_waitcnt vmcnt(28)
	v_lshlrev_b32_e32 v20, 16, v53
	v_and_b32_e32 v21, 0xffff0000, v53
	ds_bpermute_b32 v53, v28, v20
	ds_bpermute_b32 v23, v28, v21
	s_waitcnt lgkmcnt(0)
	v_mul_f32_e32 v20, v20, v88
	v_mul_f32_e32 v21, v21, v89
	v_fmac_f32_e32 v20, v90, v53
	v_fmac_f32_e32 v21, v91, v23
	v_cvt_pk_bf16_f32 v22, v20, v21
	v_add_co_u32_e32 v20, vcc, 0xa002000, v18
	s_nop 1
	v_addc_co_u32_e32 v21, vcc, 0, v19, vcc
	global_store_dword v[20:21], v22, off offset:1280
	s_waitcnt vmcnt(28)
	v_lshlrev_b32_e32 v20, 16, v52
	v_and_b32_e32 v21, 0xffff0000, v52
	ds_bpermute_b32 v52, v28, v20
	s_waitcnt lgkmcnt(1)
	ds_bpermute_b32 v23, v28, v21
	s_and_saveexec_b64 s[2:3], s[12:13]
	s_xor_b64 s[18:19], exec, s[2:3]
	s_cbranch_execz .LBB0_254
	s_and_saveexec_b64 s[30:31], s[14:15]
	s_cbranch_execz .LBB0_253
	v_mov_b32_e32 v22, v21
	s_waitcnt lgkmcnt(0)
	v_mul_f32_e32 v20, v212, v20
	v_mul_f32_e32 v21, v214, v22
	v_fmac_f32_e32 v20, v213, v52
	v_fmac_f32_e32 v21, v215, v23

; DI unsigned pk2(float lo, float hi) { f32x2 x = {lo, hi}; return __builtin_bit_cast(unsigned, __builtin_convertvector(x, bf16x2_t)); }
; DI float sum16(float v) { v += __shfl_xor(v, 8); v += __shfl_xor(v, 4); v += __shfl_xor(v, 2); v += __shfl_xor(v, 1); return v; }
; DI void post_unit(const Params& p, int l, int unit, LAS unsigned char* lds) {
;     ...
;       } else {
;         const float* gn = (s < 14) ? qnc : knc;
;         const float rs = rsqrtf(sum16(x[0] * x[0] + x[1] * x[1]) * (1.0f / 32.0f) + EPS);
;         x[0] *= rs * gn[2 * hl16]; x[1] *= rs * gn[2 * hl16 + 1]; rope2<2>(x, hl16, cs8 + t * 4);
;         if (s < 14) x *= LOG2E * 0.17677669529663687f;
;         *(unsigned*)pp = pk2(x[0], x[1]);
.LBB0_296:
	s_or_b64 exec, exec, s[18:19]
	s_mov_b32 s2, 0x3e8293ee
	s_waitcnt lgkmcnt(0)
	v_pk_mul_f32 v[20:21], v[22:23], s[2:3] op_sel_hi:[1,0]
	s_nop 0
	v_cvt_pk_bf16_f32 v22, v20, v21
	v_add_co_u32_e32 v20, vcc, 0xa003000, v18
	s_nop 1
	v_addc_co_u32_e32 v21, vcc, 0, v19, vcc
	global_store_dword v[20:21], v22, off offset:896
	s_waitcnt vmcnt(27)
	v_lshlrev_b32_e32 v20, 16, v42
	v_and_b32_e32 v21, 0xffff0000, v42
	v_pk_mul_f32 v[22:23], v[20:21], v[20:21]
	s_nop 0
	v_add_f32_e32 v22, v22, v23
	s_nop 1
	v_add_f32_dpp v22, v22, v22 row_ror:8 row_mask:0xf bank_mask:0xf
	s_nop 1
	v_add_f32_dpp v22, v22, v22 row_ror:4 row_mask:0xf bank_mask:0xf
	s_nop 1
	v_add_f32_dpp v22, v22, v22 quad_perm:[2,3,0,1] row_mask:0xf bank_mask:0xf
	s_nop 1
	v_add_f32_dpp v22, v22, v22 quad_perm:[1,0,3,2] row_mask:0xf bank_mask:0xf
	v_fmamk_f32 v22, v22, 0x3d000000, v170
	v_cmp_gt_f32_e32 vcc, s33, v22
	v_mul_f32_e32 v23, 0x4b800000, v22
	s_nop 0
	v_cndmask_b32_e32 v22, v22, v23, vcc
	v_rsq_f32_e32 v22, v22
	s_nop 0
	v_mul_f32_e32 v23, 0x45800000, v22
	v_cndmask_b32_e32 v22, v22, v23, vcc
	v_pk_mul_f32 v[22:23], v[6:7], v[22:23] op_sel_hi:[1,0]
	s_nop 0
	v_pk_mul_f32 v[22:23], v[22:23], v[20:21]
	ds_bpermute_b32 v20, v29, v22
	ds_bpermute_b32 v21, v29, v23
	s_waitcnt lgkmcnt(0)
	v_mul_f32_e32 v22, v22, v92
	v_mul_f32_e32 v23, v23, v93
	v_fmac_f32_e32 v22, v94, v20
	v_fmac_f32_e32 v23, v95, v21
	s_mov_b32 s2, 0x3e8293ee
	s_waitcnt lgkmcnt(0)
	v_pk_mul_f32 v[20:21], v[22:23], s[2:3] op_sel_hi:[1,0]
	s_nop 0
	v_cvt_pk_bf16_f32 v22, v20, v21
	v_add_co_u32_e32 v20, vcc, 0xa003000, v18
	s_nop 1
	v_addc_co_u32_e32 v21, vcc, 0, v19, vcc
	global_store_dword v[20:21], v22, off offset:1152
	s_waitcnt vmcnt(27)
	v_lshlrev_b32_e32 v20, 16, v41
	v_and_b32_e32 v21, 0xffff0000, v41
	v_pk_mul_f32 v[22:23], v[20:21], v[20:21]
	s_nop 0
	v_add_f32_e32 v22, v22, v23
	s_nop 1
	v_add_f32_dpp v22, v22, v22 row_ror:8 row_mask:0xf bank_mask:0xf
	s_nop 1
	v_add_f32_dpp v22, v22, v22 row_ror:4 row_mask:0xf bank_mask:0xf
	s_nop 1
	v_add_f32_dpp v22, v22, v22 quad_perm:[2,3,0,1] row_mask:0xf bank_mask:0xf
	s_nop 1
	v_add_f32_dpp v22, v22, v22 quad_perm:[1,0,3,2] row_mask:0xf bank_mask:0xf
	v_fmamk_f32 v22, v22, 0x3d000000, v170
	v_cmp_gt_f32_e32 vcc, s33, v22
	v_mul_f32_e32 v23, 0x4b800000, v22
	s_nop 0
	v_cndmask_b32_e32 v22, v22, v23, vcc
	v_rsq_f32_e32 v22, v22
	s_nop 0
	v_mul_f32_e32 v23, 0x45800000, v22
	v_cndmask_b32_e32 v22, v22, v23, vcc
	v_pk_mul_f32 v[22:23], v[8:9], v[22:23] op_sel_hi:[1,0]
	s_nop 0
	v_pk_mul_f32 v[22:23], v[22:23], v[20:21]
	ds_bpermute_b32 v20, v29, v22
	ds_bpermute_b32 v21, v29, v23
	s_waitcnt lgkmcnt(0)
	v_mul_f32_e32 v22, v22, v92
	v_mul_f32_e32 v23, v23, v93
	v_fmac_f32_e32 v22, v94, v20
	v_fmac_f32_e32 v23, v95, v21
	s_waitcnt lgkmcnt(1)
	v_add_co_u32_e32 v20, vcc, 0xa003000, v18
	v_cvt_pk_bf16_f32 v22, v22, v23
	s_waitcnt lgkmcnt(0)
	v_addc_co_u32_e32 v21, vcc, 0, v19, vcc
	global_store_dword v[20:21], v22, off offset:1408
	s_waitcnt vmcnt(27)
	v_lshlrev_b32_e32 v20, 16, v3
	v_and_b32_e32 v21, 0xffff0000, v3
	v_pk_mul_f32 v[22:23], v[20:21], v[20:21]
	s_nop 0
	v_add_f32_e32 v3, v22, v23
	s_nop 1
	v_add_f32_dpp v3, v3, v3 row_ror:8 row_mask:0xf bank_mask:0xf
	s_nop 1
	v_add_f32_dpp v3, v3, v3 row_ror:4 row_mask:0xf bank_mask:0xf
	s_nop 1
	v_add_f32_dpp v3, v3, v3 quad_perm:[2,3,0,1] row_mask:0xf bank_mask:0xf
	s_nop 1
	v_add_f32_dpp v3, v3, v3 quad_perm:[1,0,3,2] row_mask:0xf bank_mask:0xf
	v_fmamk_f32 v3, v3, 0x3d000000, v170
	v_cmp_gt_f32_e32 vcc, s33, v3
	v_mul_f32_e32 v22, 0x4b800000, v3
	s_nop 0
	v_cndmask_b32_e32 v3, v3, v22, vcc
	v_rsq_f32_e32 v3, v3
	s_nop 0
	v_mul_f32_e32 v22, 0x45800000, v3
	v_cndmask_b32_e32 v22, v3, v22, vcc
	v_pk_mul_f32 v[22:23], v[8:9], v[22:23] op_sel_hi:[1,0]
	s_nop 0
	v_pk_mul_f32 v[22:23], v[22:23], v[20:21]
	ds_bpermute_b32 v3, v29, v22
	ds_bpermute_b32 v21, v29, v23
	s_and_saveexec_b64 s[2:3], s[6:7]
	s_xor_b64 s[18:19], exec, s[2:3]
	s_cbranch_execz .LBB0_312
	s_and_saveexec_b64 s[30:31], s[8:9]
	s_cbranch_execz .LBB0_311
	v_mov_b32_e32 v20, v23
	s_waitcnt lgkmcnt(0)
	v_mul_f32_e32 v22, v22, v228
	v_mul_f32_e32 v23, v20, v230
	v_fmac_f32_e32 v22, v229, v3
	v_fmac_f32_e32 v23, v21, v231
